# grid barrier: leaders post the local release before their own L1 invalidate (on top of early invalidate for non-leaders)
# speedup vs baseline: 1.0173x; 1.0014x over previous
.LBB0_571:
	s_or_b64 exec, exec, s[8:9]
	s_mov_b64 s[8:9], exec
	v_mbcnt_lo_u32_b32 v0, s8, 0
	v_mbcnt_hi_u32_b32 v0, s9, v0
	v_cmp_eq_u32_e32 vcc, 0, v0
	s_waitcnt vmcnt(0)
	s_and_saveexec_b64 s[10:11], vcc
	s_cbranch_execz .LBB0_573
	s_bcnt1_i32_b64 s8, s[8:9]
	v_mov_b32_e32 v0, s8
	v_readlane_b32 s8, v253, 11
	v_readlane_b32 s9, v253, 12
	s_nop 4
	global_atomic_add v157, v0, s[8:9]
.LBB0_573:
	s_or_b64 exec, exec, s[10:11]
	buffer_inv sc1
	s_waitcnt vmcnt(0)
